# attention tile loop hand-scheduled: query blocks A and B half a step apart inside each wave (softmax VALU of one block beside the MFMAs of the other), K fragments partly re-read, V fragments read once
# baseline (speedup 1.0000x reference)
; #define PH_BEGIN(k) if (lo <= (k) && (k) < hi && ((k) < PH_LIMIT || (k) == 29) && PH_ON((k) == 0 ? 0 : ((k) == 29 ? 15 : (k) - pb + 1))) {
; #define PH_END(k) if ((k) + 1 < hi) { if ((k) == 0) grid.sync(); else { xcd_barrier(bar); xcd_barrier(bar); } } }
; #define PH_END(k) if ((k) + 1 < hi) { if ((k) == 0) grid.sync(); else xcd_barrier(bar); } }
; __global__ void __launch_bounds__(512, 2) mk_fwd(KArgs a) {
;     ...
;     for (int l = 0; l < 2; ++l) {
;         const int pb = 1 + 14 * l;
;         const float* mod = MOD + (size_t)l * 5 * NMOD;
;         const float* xl_in = l == 0 ? a.in[0] : XL; const float* xc_in = l == 0 ? a.in[2] : XC;
;         const float* dfw = a.in[13] + l * 8; const float* dbw = a.in[14] + l * 8;
;         const int ML = l == 1 ? TL : MR;
;         const bool early_conv = gridDim.x == 256;
;         PH_BEGIN(pb + 0) if (l > 0) phase_conv(a, lds, l, early_conv ? 2 : 0, 0); phase_norm(xl_in, xc_in, mod, 0, XN); PH_END(pb + 0)
.LBB0_1080:
	v_mov_b64_e32 v[190:191], 0x200
	v_mov_b64_e32 v[192:193], 0x1ff
	v_mov_b32_e32 v207, 0x358637bd
	v_mov_b32_e32 v208, 0x260
	v_mov_b32_e32 v209, 1
	v_mov_b32_e32 v211, 0xfff4bc00
	v_mov_b32_e32 v216, 0x3f317218
	v_mov_b32_e32 v217, 0x3fb8aa3b
	v_mov_b32_e32 v218, 0x7f800000
	v_readlane_b32 s4, v252, 43
	v_readlane_b32 s6, v255, 32
	v_readlane_b32 s5, v252, 44
	v_readlane_b32 s7, v255, 33
	s_or_b64 s[4:5], s[4:5], s[6:7]
	v_readlane_b32 s6, v252, 52
	v_readlane_b32 s7, v252, 53
	s_or_b64 s[4:5], s[4:5], s[6:7]
	s_and_b64 vcc, exec, s[4:5]
	v_readlane_b32 s8, v255, 4
	v_readlane_b32 s9, v255, 3
	s_cbranch_vccz .LBB0_1129

; #define MFMA32(a, b, c) __builtin_amdgcn_mfma_f32_32x32x16_bf16((a), (b), (c), 0, 0, 0)
; __device__ __forceinline__ void attn_unit2(const bf16_t* Qm, const bf16_t* KVm, const bf16_t* P1, bf16_t* OP, int q0, int h, int klat, int nlat, int kctx, int nt, uchar* lds, bool nostore = false) {
;     ...
;     for (int t = 0; t < nt; ++t) {
;         const int buf = t & 1;
;         if (t + 1 < nt) LOADKV(t + 1);
;         f32x16 sA0 = {}, sA1 = {}, sB0 = {}, sB1 = {};
;         { const uchar* kb = Kt + buf * KT_BYTES + l32 * KROW + hi * 16;
; #pragma unroll
;           for (int s = 0; s < 6; ++s) { const bf16x8 a0 = *(const bf16x8*)(kb + s * 32), a1 = *(const bf16x8*)(kb + 32 * KROW + s * 32);
;               sA0 = MFMA32(a0, qa[s], sA0); sA1 = MFMA32(a1, qa[s], sA1); sB0 = MFMA32(a0, qb[s], sB0); sB1 = MFMA32(a1, qb[s], sB1); } }
.LBB0_1103:
	s_cmpk_lg_i32 s9, 0x83
	s_cselect_b64 s[44:45], -1, 0
	s_and_b32 s4, s9, 1
	s_mul_i32 s5, s4, 0x3400
	v_add_u32_e32 v207, s5, v226
	ds_read_b128 v[234:237], v207 offset:176
	ds_read_b128 v[238:241], v207 offset:6832
	ds_read_b128 v[242:245], v207
	ds_read_b128 v[246:249], v207 offset:6656
	ds_read_b128 v[208:211], v207 offset:32
	ds_read_b128 v[212:215], v207 offset:6688
	ds_read_b128 v[198:201], v207 offset:64
	ds_read_b128 v[202:205], v207 offset:6720
	ds_read_b128 v[98:101], v207 offset:96
	ds_read_b128 v[66:69], v207 offset:6752
	ds_read_b128 v[102:105], v207 offset:128
	ds_read_b128 v[70:73], v207 offset:6784
	ds_read_b128 v[106:109], v207 offset:160
	ds_read_b128 v[74:77], v207 offset:6816
	s_cmpk_eq_i32 s9, 0x83
	s_cbranch_scc1 .Lq_lddone
	s_cmpk_lt_u32 s9, 0x7f
	s_cselect_b32 s6, s22, s13
	s_mul_i32 s18, s6, s16
	s_add_u32 s18, s18, s82
	s_addc_u32 s19, s83, 0
	s_add_u32 s18, s18, s30
	s_addc_u32 s19, s19, s31
	s_lshl_b32 s6, s6, 11
	s_add_u32 s6, s6, s74
	s_add_u32 s6, s92, s6
	s_addc_u32 s7, s93, 0
	s_mov_b64 exec, s[38:39]
	global_load_dwordx4 v[178:181], v196, s[18:19]
	s_not_b64 exec, exec
	global_load_dwordx4 v[178:181], v196, s[6:7]
	s_cmp_lg_u64 s[40:41], 0
	s_cbranch_scc1 .Lq_ldv
	s_mov_b64 exec, s[42:43]
	global_load_dwordx4 v[186:189], v197, s[18:19]
	s_not_b64 exec, exec
	global_load_dwordx4 v[186:189], v197, s[6:7]
	s_mov_b64 exec, -1
	s_branch .Lq_lddone
.Lq_ldv:
	s_mov_b64 exec, -1
	global_load_dwordx4 v[182:185], v197, s[6:7] offset:2048
	global_load_dwordx4 v[186:189], v197, s[6:7]
.Lq_lddone:
	s_waitcnt lgkmcnt(13)
	v_mfma_f32_32x32x16_bf16 v[114:129], v[234:237], v[216:219], 0
	s_waitcnt lgkmcnt(12)
	v_mfma_f32_32x32x16_bf16 v[82:97], v[238:241], v[216:219], 0
	s_waitcnt lgkmcnt(11)
	v_mfma_f32_32x32x16_bf16 v[114:129], v[242:245], v[130:133], v[114:129]
	s_waitcnt lgkmcnt(10)
	v_mfma_f32_32x32x16_bf16 v[82:97], v[246:249], v[130:133], v[82:97]
	s_waitcnt lgkmcnt(9)
	v_mfma_f32_32x32x16_bf16 v[114:129], v[208:211], v[134:137], v[114:129]
	s_waitcnt lgkmcnt(8)
	v_mfma_f32_32x32x16_bf16 v[82:97], v[212:215], v[134:137], v[82:97]
	s_waitcnt lgkmcnt(7)
	v_mfma_f32_32x32x16_bf16 v[114:129], v[198:201], v[146:149], v[114:129]
	s_waitcnt lgkmcnt(6)
	v_mfma_f32_32x32x16_bf16 v[82:97], v[202:205], v[146:149], v[82:97]
	s_waitcnt lgkmcnt(5)
	v_mfma_f32_32x32x16_bf16 v[114:129], v[98:101], v[150:153], v[114:129]
	s_waitcnt lgkmcnt(4)
	v_mfma_f32_32x32x16_bf16 v[82:97], v[66:69], v[150:153], v[82:97]
	s_waitcnt lgkmcnt(3)
	v_mfma_f32_32x32x16_bf16 v[114:129], v[102:105], v[162:165], v[114:129]
	s_waitcnt lgkmcnt(2)
	v_mfma_f32_32x32x16_bf16 v[82:97], v[70:73], v[162:165], v[82:97]
	s_waitcnt lgkmcnt(1)
	v_mfma_f32_32x32x16_bf16 v[114:129], v[106:109], v[166:169], v[114:129]
	s_waitcnt lgkmcnt(0)
	v_mfma_f32_32x32x16_bf16 v[82:97], v[74:77], v[166:169], v[82:97]
	v_mfma_f32_32x32x16_bf16 v[98:113], v[234:237], v[190:193], 0
	ds_read_b128 v[234:237], v207 offset:96
	v_mfma_f32_32x32x16_bf16 v[66:81], v[238:241], v[190:193], 0
	ds_read_b128 v[238:241], v207 offset:6752
	v_mfma_f32_32x32x16_bf16 v[98:113], v[242:245], v[170:173], v[98:113]
	ds_read_b128 v[242:245], v207 offset:128
	v_mfma_f32_32x32x16_bf16 v[66:81], v[246:249], v[170:173], v[66:81]
	ds_read_b128 v[246:249], v207 offset:6784
	s_nop 1
	v_max3_f32 v221, v114, v115, v116
	v_max3_f32 v223, v117, v118, v119
	v_max3_f32 v221, v221, v120, v121
	v_max3_f32 v223, v223, v122, v123
	v_max3_f32 v221, v221, v124, v125
	v_max3_f32 v223, v223, v126, v127
	v_max3_f32 v221, v221, v128, v129
	v_max3_f32 v223, v223, v82, v83
	v_max3_f32 v221, v221, v84, v85
	v_max3_f32 v223, v223, v86, v87
	v_max3_f32 v221, v221, v88, v89
	v_mfma_f32_32x32x16_bf16 v[98:113], v[208:211], v[138:141], v[98:113]
	ds_read_b128 v[208:211], v207 offset:160
	v_max3_f32 v223, v223, v90, v91
	v_max3_f32 v221, v221, v92, v93
	v_max3_f32 v223, v223, v94, v95
	v_max3_f32 v221, v221, v96, v97
	v_max_f32_e32 v221, v221, v223
	v_cmp_lt_f32_e32 vcc, 0x41000000, v221
	s_cmp_eq_u32 s9, 0
	s_cbranch_scc1 .Lq_rareA
	s_cbranch_vccz .Lq_contA
.Lq_rareA:
	ds_bpermute_b32 v195, v227, v221
	s_waitcnt lgkmcnt(0)
	v_max_f32_e32 v221, v221, v195
	s_cmp_eq_u32 s9, 0
	s_cbranch_scc1 .Lq_rareA1
	v_max_f32_e32 v221, 0, v221
.Lq_rareA1:
	v_add_f32_e32 v223, v232, v221
	v_and_b32_e32 v223, 0xffff0000, v223
	v_sub_f32_e32 v195, v223, v232
	v_mov_b32_e32 v232, v223
	v_xor_b32_e32 v223, 0x80000000, v223
	v_lshrrev_b32_e32 v223, 16, v223
	s_mov_b32 exec_lo, 0
	v_mov_b32_e32 v216, v223
	s_mov_b32 exec_lo, -1
	v_sub_f32_e32 v0, 0, v195
	v_min_f32_e32 v0, 0x42800000, v0
	v_exp_f32_e32 v0, v0
	v_sub_f32_e32 v114, v114, v195
	v_sub_f32_e32 v115, v115, v195
	v_sub_f32_e32 v116, v116, v195
	v_sub_f32_e32 v117, v117, v195
	v_sub_f32_e32 v118, v118, v195
	v_sub_f32_e32 v119, v119, v195
	v_sub_f32_e32 v120, v120, v195
	v_sub_f32_e32 v121, v121, v195
	v_sub_f32_e32 v122, v122, v195
	v_sub_f32_e32 v123, v123, v195
	v_sub_f32_e32 v124, v124, v195
	v_sub_f32_e32 v125, v125, v195
	v_sub_f32_e32 v126, v126, v195
	v_sub_f32_e32 v127, v127, v195
	v_sub_f32_e32 v128, v128, v195
	v_sub_f32_e32 v129, v129, v195
	v_sub_f32_e32 v82, v82, v195
	v_sub_f32_e32 v83, v83, v195
	v_sub_f32_e32 v84, v84, v195
	v_sub_f32_e32 v85, v85, v195
	v_sub_f32_e32 v86, v86, v195
	v_sub_f32_e32 v87, v87, v195
	v_sub_f32_e32 v88, v88, v195
	v_sub_f32_e32 v89, v89, v195
	v_sub_f32_e32 v90, v90, v195
	v_sub_f32_e32 v91, v91, v195
	v_sub_f32_e32 v92, v92, v195
	v_sub_f32_e32 v93, v93, v195
	v_sub_f32_e32 v94, v94, v195
	v_sub_f32_e32 v95, v95, v195
	v_sub_f32_e32 v96, v96, v195
	v_sub_f32_e32 v97, v97, v195
	v_mul_f32_e32 v231, v231, v0
	v_pk_mul_f32 v[64:65], v[64:65], v[0:1] op_sel_hi:[1,0]
	v_pk_mul_f32 v[62:63], v[62:63], v[0:1] op_sel_hi:[1,0]
	v_pk_mul_f32 v[60:61], v[60:61], v[0:1] op_sel_hi:[1,0]
	v_pk_mul_f32 v[58:59], v[58:59], v[0:1] op_sel_hi:[1,0]
	v_pk_mul_f32 v[56:57], v[56:57], v[0:1] op_sel_hi:[1,0]
	v_pk_mul_f32 v[54:55], v[54:55], v[0:1] op_sel_hi:[1,0]
	v_pk_mul_f32 v[52:53], v[52:53], v[0:1] op_sel_hi:[1,0]
	v_pk_mul_f32 v[50:51], v[50:51], v[0:1] op_sel_hi:[1,0]
	v_pk_mul_f32 v[48:49], v[48:49], v[0:1] op_sel_hi:[1,0]
	v_pk_mul_f32 v[46:47], v[46:47], v[0:1] op_sel_hi:[1,0]
	v_pk_mul_f32 v[44:45], v[44:45], v[0:1] op_sel_hi:[1,0]
	v_pk_mul_f32 v[42:43], v[42:43], v[0:1] op_sel_hi:[1,0]
	v_pk_mul_f32 v[40:41], v[40:41], v[0:1] op_sel_hi:[1,0]
	v_pk_mul_f32 v[38:39], v[38:39], v[0:1] op_sel_hi:[1,0]
	v_pk_mul_f32 v[36:37], v[36:37], v[0:1] op_sel_hi:[1,0]
	v_pk_mul_f32 v[34:35], v[34:35], v[0:1] op_sel_hi:[1,0]
; #define MFMA32(a, b, c) __builtin_amdgcn_mfma_f32_32x32x16_bf16((a), (b), (c), 0, 0, 0)
; __device__ __forceinline__ void attn_unit2(const bf16_t* Qm, const bf16_t* KVm, const bf16_t* P1, bf16_t* OP, int q0, int h, int klat, int nlat, int kctx, int nt, uchar* lds, bool nostore = false) {
;     ...
;         SOFTMAX_BLK(sA0, sA1, mA, lA, oA0, oA1);
;         SOFTMAX_BLK(sB0, sB1, mB, lB, oB0, oB1);
;         const uchar* vb = Vt + buf * VT_BYTES + l32 * VROW + hi * 16;
; #pragma unroll
;         for (int kk = 0; kk < 4; ++kk) {
;             const int r0 = 8 * (kk & 1);
;             const bf16x8 pa = (kk >> 1) ? pack8(sA1[r0], sA1[r0 + 1], sA1[r0 + 2], sA1[r0 + 3], sA1[r0 + 4], sA1[r0 + 5], sA1[r0 + 6], sA1[r0 + 7])
;                                         : pack8(sA0[r0], sA0[r0 + 1], sA0[r0 + 2], sA0[r0 + 3], sA0[r0 + 4], sA0[r0 + 5], sA0[r0 + 6], sA0[r0 + 7]);
;             const bf16x8 pb = (kk >> 1) ? pack8(sB1[r0], sB1[r0 + 1], sB1[r0 + 2], sB1[r0 + 3], sB1[r0 + 4], sB1[r0 + 5], sB1[r0 + 6], sB1[r0 + 7])
;                                         : pack8(sB0[r0], sB0[r0 + 1], sB0[r0 + 2], sB0[r0 + 3], sB0[r0 + 4], sB0[r0 + 5], sB0[r0 + 6], sB0[r0 + 7]);
;             const bf16x8 a0 = *(const bf16x8*)(vb + kk * 32), a1 = *(const bf16x8*)(vb + 32 * VROW + kk * 32);
;             oA0 = MFMA32(a0, pa, oA0); oA1 = MFMA32(a1, pa, oA1); oB0 = MFMA32(a0, pb, oB0); oB1 = MFMA32(a1, pb, oB1);
;         }
.Lq_contA:
	v_mfma_f32_32x32x16_bf16 v[66:81], v[212:215], v[138:141], v[66:81]
	ds_read_b128 v[212:215], v207 offset:6816
	v_exp_f32_e32 v114, v114
	v_exp_f32_e32 v115, v115
	v_exp_f32_e32 v116, v116
	v_exp_f32_e32 v117, v117
	v_exp_f32_e32 v118, v118
	v_exp_f32_e32 v119, v119
	v_exp_f32_e32 v120, v120
	v_exp_f32_e32 v121, v121
	v_add_f32_e32 v221, v114, v115
	v_add_f32_e32 v223, v116, v117
	v_add_f32_e32 v221, v223, v221
	v_mfma_f32_32x32x16_bf16 v[98:113], v[198:201], v[142:145], v[98:113]
	v_add_f32_e32 v223, v118, v119
	v_add_f32_e32 v221, v223, v221
	v_add_f32_e32 v223, v120, v121
	v_add_f32_e32 v221, v223, v221
	v_cvt_pk_bf16_f32 v114, v114, v115
	v_cvt_pk_bf16_f32 v115, v116, v117
	v_cvt_pk_bf16_f32 v116, v118, v119
	v_cvt_pk_bf16_f32 v117, v120, v121
	v_exp_f32_e32 v122, v122
	v_exp_f32_e32 v123, v123
	v_exp_f32_e32 v124, v124
	v_mfma_f32_32x32x16_bf16 v[66:81], v[202:205], v[142:145], v[66:81]
	v_exp_f32_e32 v125, v125
	v_exp_f32_e32 v126, v126
	v_exp_f32_e32 v127, v127
	v_exp_f32_e32 v128, v128
	v_exp_f32_e32 v129, v129
	v_add_f32_e32 v223, v122, v123
	v_add_f32_e32 v221, v223, v221
	v_add_f32_e32 v223, v124, v125
	v_add_f32_e32 v221, v223, v221
	v_add_f32_e32 v223, v126, v127
	v_add_f32_e32 v221, v223, v221
	s_waitcnt lgkmcnt(5)
	v_mfma_f32_32x32x16_bf16 v[98:113], v[234:237], v[154:157], v[98:113]
	v_add_f32_e32 v223, v128, v129
	v_add_f32_e32 v221, v223, v221
	v_cvt_pk_bf16_f32 v122, v122, v123
	v_cvt_pk_bf16_f32 v123, v124, v125
	v_cvt_pk_bf16_f32 v124, v126, v127
	v_cvt_pk_bf16_f32 v125, v128, v129
	v_exp_f32_e32 v82, v82
	v_exp_f32_e32 v83, v83
	v_exp_f32_e32 v84, v84
	v_exp_f32_e32 v85, v85
	v_exp_f32_e32 v86, v86
	s_waitcnt lgkmcnt(4)
	v_mfma_f32_32x32x16_bf16 v[66:81], v[238:241], v[154:157], v[66:81]
	v_exp_f32_e32 v87, v87
	v_exp_f32_e32 v88, v88
	v_exp_f32_e32 v89, v89
	v_add_f32_e32 v223, v82, v83
	v_add_f32_e32 v221, v223, v221
	v_add_f32_e32 v223, v84, v85
	v_add_f32_e32 v221, v223, v221
	v_add_f32_e32 v223, v86, v87
	v_add_f32_e32 v221, v223, v221
	v_add_f32_e32 v223, v88, v89
	v_add_f32_e32 v221, v223, v221
	s_waitcnt lgkmcnt(3)
	v_mfma_f32_32x32x16_bf16 v[98:113], v[242:245], v[158:161], v[98:113]
	v_cvt_pk_bf16_f32 v82, v82, v83
	v_cvt_pk_bf16_f32 v83, v84, v85
	v_cvt_pk_bf16_f32 v84, v86, v87
	v_cvt_pk_bf16_f32 v85, v88, v89
	v_exp_f32_e32 v90, v90
	v_exp_f32_e32 v91, v91
	v_exp_f32_e32 v92, v92
	v_exp_f32_e32 v93, v93
	v_exp_f32_e32 v94, v94
	v_exp_f32_e32 v95, v95
	v_exp_f32_e32 v96, v96
	s_waitcnt lgkmcnt(2)
	v_mfma_f32_32x32x16_bf16 v[66:81], v[246:249], v[158:161], v[66:81]
	v_exp_f32_e32 v97, v97
	v_add_f32_e32 v223, v90, v91
	v_add_f32_e32 v221, v223, v221
	v_add_f32_e32 v223, v92, v93
	v_add_f32_e32 v221, v223, v221
	v_add_f32_e32 v223, v94, v95
	v_add_f32_e32 v221, v223, v221
	v_add_f32_e32 v223, v96, v97
	v_add_f32_e32 v221, v223, v221
	v_cvt_pk_bf16_f32 v90, v90, v91
	v_cvt_pk_bf16_f32 v91, v92, v93
	s_waitcnt lgkmcnt(1)
	v_mfma_f32_32x32x16_bf16 v[98:113], v[208:211], v[174:177], v[98:113]
	v_cvt_pk_bf16_f32 v92, v94, v95
	v_cvt_pk_bf16_f32 v93, v96, v97
	v_add_f32_e32 v231, v231, v221
	s_waitcnt lgkmcnt(0)
	v_mfma_f32_32x32x16_bf16 v[66:81], v[212:215], v[174:177], v[66:81]
	s_mul_i32 s5, s4, 0x2400
	v_add_u32_e32 v207, s5, v228
	ds_read_b128 v[234:237], v207 offset:26624
	ds_read_b128 v[238:241], v207 offset:31232
	ds_read_b128 v[242:245], v207 offset:26656
	ds_read_b128 v[246:249], v207 offset:31264
	ds_read_b128 v[208:211], v207 offset:26688
	ds_read_b128 v[212:215], v207 offset:31296
	ds_read_b128 v[198:201], v207 offset:26720
	ds_read_b128 v[202:205], v207 offset:31328
	s_waitcnt lgkmcnt(7)
	v_mfma_f32_32x32x16_bf16 v[50:65], v[234:237], v[114:117], v[50:65]
	v_max3_f32 v221, v98, v99, v100
	v_max3_f32 v223, v101, v102, v103
	v_max3_f32 v221, v221, v104, v105
	v_max3_f32 v223, v223, v106, v107
	v_max3_f32 v221, v221, v108, v109
	v_max3_f32 v223, v223, v110, v111
	v_max3_f32 v221, v221, v112, v113
	v_max3_f32 v223, v223, v66, v67
	v_max3_f32 v221, v221, v68, v69
	v_max3_f32 v223, v223, v70, v71
	v_max3_f32 v221, v221, v72, v73
	v_max3_f32 v223, v223, v74, v75
	v_max3_f32 v221, v221, v76, v77
	v_max3_f32 v223, v223, v78, v79
	v_max3_f32 v221, v221, v80, v81
	v_max_f32_e32 v221, v221, v223
	v_cmp_lt_f32_e32 vcc, 0x41000000, v221
	s_cmp_eq_u32 s9, 0
	s_cbranch_scc1 .Lq_rareB
	s_cbranch_vccz .Lq_contB

; #define MFMA32(a, b, c) __builtin_amdgcn_mfma_f32_32x32x16_bf16((a), (b), (c), 0, 0, 0)
; #define STOREKV(buf) do { *(u32x4*)(Kt + (buf) * KT_BYTES + kr0 * KROW + kc0 * 16) = xk0; \
;         if (tid < 256) { *(u32x4*)(Kt + (buf) * KT_BYTES + kr1 * KROW + kc1 * 16) = xa; } \
;         else { tstore_pair(Vt + (buf) * VT_BYTES, VROW, pos64(2 * va), vc8, xa, xb); } } while (0)
; __device__ __forceinline__ void attn_unit2(const bf16_t* Qm, const bf16_t* KVm, const bf16_t* P1, bf16_t* OP, int q0, int h, int klat, int nlat, int kctx, int nt, uchar* lds, bool nostore = false) {
;     ...
;         SOFTMAX_BLK(sA0, sA1, mA, lA, oA0, oA1);
;         SOFTMAX_BLK(sB0, sB1, mB, lB, oB0, oB1);
;         const uchar* vb = Vt + buf * VT_BYTES + l32 * VROW + hi * 16;
; #pragma unroll
;         for (int kk = 0; kk < 4; ++kk) {
;             const int r0 = 8 * (kk & 1);
;             const bf16x8 pa = (kk >> 1) ? pack8(sA1[r0], sA1[r0 + 1], sA1[r0 + 2], sA1[r0 + 3], sA1[r0 + 4], sA1[r0 + 5], sA1[r0 + 6], sA1[r0 + 7])
;                                         : pack8(sA0[r0], sA0[r0 + 1], sA0[r0 + 2], sA0[r0 + 3], sA0[r0 + 4], sA0[r0 + 5], sA0[r0 + 6], sA0[r0 + 7]);
;             const bf16x8 pb = (kk >> 1) ? pack8(sB1[r0], sB1[r0 + 1], sB1[r0 + 2], sB1[r0 + 3], sB1[r0 + 4], sB1[r0 + 5], sB1[r0 + 6], sB1[r0 + 7])
;                                         : pack8(sB0[r0], sB0[r0 + 1], sB0[r0 + 2], sB0[r0 + 3], sB0[r0 + 4], sB0[r0 + 5], sB0[r0 + 6], sB0[r0 + 7]);
;             const bf16x8 a0 = *(const bf16x8*)(vb + kk * 32), a1 = *(const bf16x8*)(vb + 32 * VROW + kk * 32);
;             oA0 = MFMA32(a0, pa, oA0); oA1 = MFMA32(a1, pa, oA1); oB0 = MFMA32(a0, pb, oB0); oB1 = MFMA32(a1, pb, oB1);
;         }
;         if (t + 1 < nt) STOREKV(buf ^ 1);
;         __syncthreads();
;     }
.Lq_rareB1:
	v_add_f32_e32 v223, v233, v221
	v_and_b32_e32 v223, 0xffff0000, v223
	v_sub_f32_e32 v195, v223, v233
	v_mov_b32_e32 v233, v223
	v_xor_b32_e32 v223, 0x80000000, v223
	v_lshrrev_b32_e32 v223, 16, v223
	s_mov_b32 exec_lo, 0
	v_mov_b32_e32 v190, v223
	s_mov_b32 exec_lo, -1
	v_sub_f32_e32 v0, 0, v195
	v_min_f32_e32 v0, 0x42800000, v0
	v_exp_f32_e32 v0, v0
	v_sub_f32_e32 v98, v98, v195
	v_sub_f32_e32 v99, v99, v195
	v_sub_f32_e32 v100, v100, v195
	v_sub_f32_e32 v101, v101, v195
	v_sub_f32_e32 v102, v102, v195
	v_sub_f32_e32 v103, v103, v195
	v_sub_f32_e32 v104, v104, v195
	v_sub_f32_e32 v105, v105, v195
	v_sub_f32_e32 v106, v106, v195
	v_sub_f32_e32 v107, v107, v195
	v_sub_f32_e32 v108, v108, v195
	v_sub_f32_e32 v109, v109, v195
	v_sub_f32_e32 v110, v110, v195
	v_sub_f32_e32 v111, v111, v195
	v_sub_f32_e32 v112, v112, v195
	v_sub_f32_e32 v113, v113, v195
	v_sub_f32_e32 v66, v66, v195
	v_sub_f32_e32 v67, v67, v195
	v_sub_f32_e32 v68, v68, v195
	v_sub_f32_e32 v69, v69, v195
	v_sub_f32_e32 v70, v70, v195
	v_sub_f32_e32 v71, v71, v195
	v_sub_f32_e32 v72, v72, v195
	v_sub_f32_e32 v73, v73, v195
	v_sub_f32_e32 v74, v74, v195
	v_sub_f32_e32 v75, v75, v195
	v_sub_f32_e32 v76, v76, v195
	v_sub_f32_e32 v77, v77, v195
	v_sub_f32_e32 v78, v78, v195
	v_sub_f32_e32 v79, v79, v195
	v_sub_f32_e32 v80, v80, v195
	v_sub_f32_e32 v81, v81, v195
	v_mul_f32_e32 v229, v229, v0
	v_pk_mul_f32 v[32:33], v[32:33], v[0:1] op_sel_hi:[1,0]
	v_pk_mul_f32 v[30:31], v[30:31], v[0:1] op_sel_hi:[1,0]
	v_pk_mul_f32 v[28:29], v[28:29], v[0:1] op_sel_hi:[1,0]
	v_pk_mul_f32 v[26:27], v[26:27], v[0:1] op_sel_hi:[1,0]
	v_pk_mul_f32 v[24:25], v[24:25], v[0:1] op_sel_hi:[1,0]
	v_pk_mul_f32 v[22:23], v[22:23], v[0:1] op_sel_hi:[1,0]
	v_pk_mul_f32 v[20:21], v[20:21], v[0:1] op_sel_hi:[1,0]
	v_pk_mul_f32 v[18:19], v[18:19], v[0:1] op_sel_hi:[1,0]
	v_pk_mul_f32 v[16:17], v[16:17], v[0:1] op_sel_hi:[1,0]
	v_pk_mul_f32 v[14:15], v[14:15], v[0:1] op_sel_hi:[1,0]
	v_pk_mul_f32 v[12:13], v[12:13], v[0:1] op_sel_hi:[1,0]
	v_pk_mul_f32 v[10:11], v[10:11], v[0:1] op_sel_hi:[1,0]
	v_pk_mul_f32 v[8:9], v[8:9], v[0:1] op_sel_hi:[1,0]
	v_pk_mul_f32 v[6:7], v[6:7], v[0:1] op_sel_hi:[1,0]
	v_pk_mul_f32 v[4:5], v[4:5], v[0:1] op_sel_hi:[1,0]
	v_pk_mul_f32 v[2:3], v[2:3], v[0:1] op_sel_hi:[1,0]
.Lq_contB:
	s_waitcnt lgkmcnt(6)
	v_mfma_f32_32x32x16_bf16 v[34:49], v[238:241], v[114:117], v[34:49]
	v_exp_f32_e32 v98, v98
	v_exp_f32_e32 v99, v99
	v_exp_f32_e32 v100, v100
	v_exp_f32_e32 v101, v101
	v_exp_f32_e32 v102, v102
	v_exp_f32_e32 v103, v103
	v_exp_f32_e32 v104, v104
	v_exp_f32_e32 v105, v105
	v_add_f32_e32 v221, v98, v99
	v_add_f32_e32 v223, v100, v101
	v_add_f32_e32 v221, v223, v221
	v_add_f32_e32 v223, v102, v103
	v_add_f32_e32 v221, v223, v221
	v_add_f32_e32 v223, v104, v105
	v_add_f32_e32 v221, v223, v221
	v_cvt_pk_bf16_f32 v98, v98, v99
	v_cvt_pk_bf16_f32 v99, v100, v101
	s_waitcnt lgkmcnt(5)
	v_mfma_f32_32x32x16_bf16 v[50:65], v[242:245], v[122:125], v[50:65]
	v_cvt_pk_bf16_f32 v100, v102, v103
	v_cvt_pk_bf16_f32 v101, v104, v105
	v_exp_f32_e32 v106, v106
	v_exp_f32_e32 v107, v107
	v_exp_f32_e32 v108, v108
	v_exp_f32_e32 v109, v109
	v_exp_f32_e32 v110, v110
	v_exp_f32_e32 v111, v111
	v_exp_f32_e32 v112, v112
	v_exp_f32_e32 v113, v113
	v_add_f32_e32 v223, v106, v107
	v_add_f32_e32 v221, v223, v221
	v_add_f32_e32 v223, v108, v109
	v_add_f32_e32 v221, v223, v221
	v_add_f32_e32 v223, v110, v111
	v_add_f32_e32 v221, v223, v221
	v_add_f32_e32 v223, v112, v113
	s_waitcnt lgkmcnt(4)
	v_mfma_f32_32x32x16_bf16 v[34:49], v[246:249], v[122:125], v[34:49]
	v_add_f32_e32 v221, v223, v221
	v_cvt_pk_bf16_f32 v106, v106, v107
	v_cvt_pk_bf16_f32 v107, v108, v109
	v_cvt_pk_bf16_f32 v108, v110, v111
	v_cvt_pk_bf16_f32 v109, v112, v113
	v_exp_f32_e32 v66, v66
	v_exp_f32_e32 v67, v67
	v_exp_f32_e32 v68, v68
	v_exp_f32_e32 v69, v69
	v_exp_f32_e32 v70, v70
	v_exp_f32_e32 v71, v71
	v_exp_f32_e32 v72, v72
	v_exp_f32_e32 v73, v73
	v_add_f32_e32 v223, v66, v67
	v_add_f32_e32 v221, v223, v221
	v_add_f32_e32 v223, v68, v69
	v_add_f32_e32 v221, v223, v221
	s_waitcnt lgkmcnt(3)
	v_mfma_f32_32x32x16_bf16 v[50:65], v[208:211], v[82:85], v[50:65]
	v_add_f32_e32 v223, v70, v71
	v_add_f32_e32 v221, v223, v221
	v_add_f32_e32 v223, v72, v73
	v_add_f32_e32 v221, v223, v221
	v_cvt_pk_bf16_f32 v66, v66, v67
	v_cvt_pk_bf16_f32 v67, v68, v69
	v_cvt_pk_bf16_f32 v68, v70, v71
	v_cvt_pk_bf16_f32 v69, v72, v73
	v_exp_f32_e32 v74, v74
	v_exp_f32_e32 v75, v75
	v_exp_f32_e32 v76, v76
	v_exp_f32_e32 v77, v77
	v_exp_f32_e32 v78, v78
	v_exp_f32_e32 v79, v79
	v_exp_f32_e32 v80, v80
	v_exp_f32_e32 v81, v81
	v_add_f32_e32 v223, v74, v75
	s_waitcnt lgkmcnt(2)
	v_mfma_f32_32x32x16_bf16 v[34:49], v[212:215], v[82:85], v[34:49]
	v_add_f32_e32 v221, v223, v221
	v_add_f32_e32 v223, v76, v77
	v_add_f32_e32 v221, v223, v221
	v_add_f32_e32 v223, v78, v79
	v_add_f32_e32 v221, v223, v221
	v_add_f32_e32 v223, v80, v81
	v_add_f32_e32 v221, v223, v221
	v_cvt_pk_bf16_f32 v74, v74, v75
	v_cvt_pk_bf16_f32 v75, v76, v77
	v_cvt_pk_bf16_f32 v76, v78, v79
	v_cvt_pk_bf16_f32 v77, v80, v81
	v_add_f32_e32 v229, v229, v221
	s_waitcnt lgkmcnt(1)
	v_mfma_f32_32x32x16_bf16 v[50:65], v[198:201], v[90:93], v[50:65]
	s_waitcnt lgkmcnt(0)
	v_mfma_f32_32x32x16_bf16 v[34:49], v[202:205], v[90:93], v[34:49]
	v_mfma_f32_32x32x16_bf16 v[18:33], v[234:237], v[98:101], v[18:33]
	v_mfma_f32_32x32x16_bf16 v[2:17], v[238:241], v[98:101], v[2:17]
	v_mfma_f32_32x32x16_bf16 v[18:33], v[242:245], v[106:109], v[18:33]
	v_mfma_f32_32x32x16_bf16 v[2:17], v[246:249], v[106:109], v[2:17]
	v_mfma_f32_32x32x16_bf16 v[18:33], v[208:211], v[66:69], v[18:33]
	v_mfma_f32_32x32x16_bf16 v[2:17], v[212:215], v[66:69], v[2:17]
	v_mfma_f32_32x32x16_bf16 v[18:33], v[198:201], v[74:77], v[18:33]
	v_mfma_f32_32x32x16_bf16 v[2:17], v[202:205], v[74:77], v[2:17]
	s_andn2_b64 vcc, exec, s[44:45]
	s_cbranch_vccnz .Lq_tail
	s_xor_b32 s7, s4, 1
	s_mul_i32 s4, s7, 0x3400
	s_add_i32 s6, s4, 0
	v_add3_u32 v207, s6, v222, v194
	s_waitcnt vmcnt(2)
	ds_write_b128 v207, v[178:181]
	s_cmp_lg_u64 s[40:41], 0
	s_cbranch_scc0 .Lq_stk
	s_mulk_i32 s7, 0x2400
	v_add_u32_e32 v207, s7, v230
	s_mov_b32 s18, 0x5040100
	s_mov_b32 s19, 0x7060302
	v_add_u32_e32 v207, 0x6800, v207
	s_waitcnt vmcnt(0)
	v_perm_b32 v221, v182, v186, s18
	v_perm_b32 v223, v182, v186, s19
	ds_write2_b32 v207, v221, v223 offset1:36
	v_perm_b32 v221, v183, v187, s18
	v_perm_b32 v223, v183, v187, s19
	ds_write2_b32 v207, v221, v223 offset0:72 offset1:108
	v_perm_b32 v221, v184, v188, s18
	v_perm_b32 v223, v184, v188, s19
	ds_write2_b32 v207, v221, v223 offset0:144 offset1:180
	v_perm_b32 v221, v185, v189, s18
	v_perm_b32 v223, v185, v189, s19
	ds_write2_b32 v207, v221, v223 offset0:216 offset1:252
	s_branch .Lq_tail
.Lq_stk:
	v_add3_u32 v207, s6, v224, v225
	s_waitcnt vmcnt(0)
	ds_write_b128 v207, v[186:189]
.Lq_tail:
	s_add_i32 s9, s9, 1
	s_add_i32 s13, s13, 64
	s_add_i32 s22, s22, 64
	s_cmpk_eq_i32 s9, 0x84
	s_waitcnt lgkmcnt(0)
	s_barrier
	s_cbranch_scc0 .LBB0_1103
